# attention item order: no per-wave rotation (every wave walks its items in order: NSA quarters 0..3 then its two memory items)
# baseline (speedup 1.0000x reference)
; __device__ __forceinline__ void attention_phase(const Ctx& C) {
;     const int bxx = C.gw / NWAVES; const bool xmode = (C.G & 7) == 0;
;     const int x = bxx & 7, rank = xmode ? (bxx >> 3) * NWAVES + C.wave : C.gw, nrank = xmode ? (C.G >> 3) * NWAVES : C.NGW, nitem = xmode ? 1536 : 12288;
;     const int nper = (nitem + nrank - 1) / nrank, nmem_it = xmode ? (512 + nrank - 1) / nrank : 0; const bool flip = xmode && (nitem % nrank == 0); const int rot = flip ? ((C.wave * 3) >> 3) * 2 : 0;
;     for (int k0 = 0; k0 < nper; ++k0) {
;         const int kk = flip ? (k0 + rot) % nper : k0; const int i = rank + kk * nrank; if (i >= nitem) continue;
.LBB0_646:
	v_readlane_b32 s2, v254, 30
	v_readlane_b32 s3, v254, 31
	s_andn2_b64 vcc, exec, s[2:3]
	s_cbranch_vccnz .LBB0_886
	s_ashr_i32 s2, s1, 6
	s_lshl_b32 s0, s0, 3
	s_add_i32 s3, s0, s2
	s_ashr_i32 s0, s3, 31
	s_lshr_b32 s0, s0, 29
	s_add_i32 s0, s3, s0
	s_mul_i32 s1, s2, 3
	s_ashr_i32 s4, s0, 3
	s_ashr_i32 s1, s1, 2
	s_and_b32 s0, s4, -8
	s_mov_b32 s8, 0
	s_add_i32 s5, s0, s2
	v_readlane_b32 s0, v254, 3
	v_readlane_b32 s1, v254, 4
	s_and_b64 s[0:1], s[0:1], exec
	s_cselect_b32 s9, s5, s3
	s_lshl_b32 s0, s4, 10
	s_and_b32 s0, s0, 0x1800
	s_and_b32 s1, s4, 1
	s_or_b32 s71, s0, s1
	s_lshl_b32 s0, s4, 9
	s_and_b32 s72, s0, 0xe00
	s_addk_i32 s72, 0xfc00
	s_add_u32 s86, s34, 0x10200000
	s_mulk_i32 s2, 0x4100
	s_addc_u32 s87, s35, 0
	s_add_i32 s73, s2, 0
	s_add_u32 s74, s34, 0x3d00000
	s_addc_u32 s75, s35, 0
	s_add_u32 s28, s34, 0x3d80000
	s_addc_u32 s77, s35, 0
	s_add_u32 s90, s34, 0x4200000
	s_addc_u32 s91, s35, 0
	s_add_u32 s94, s34, 0x4a00000
	s_addc_u32 s95, s35, 0
	s_add_u32 s78, s34, 0x3a00000
	s_addc_u32 s79, s35, 0
	s_add_u32 s29, s34, 0x5200000
	s_addc_u32 s37, s35, 0
	s_add_u32 s59, s34, 0x5a00000
	v_and_b32_e32 v252, 63, v0
	s_addc_u32 s80, s35, 0
	s_mov_b32 s96, 0
	s_branch .LBB0_651
